# NA item order permuted so the 8 row blocks of one (batch, head) K/V slice run concurrently on workgroups of one XCD (L2 sharing); same items, same work
# speedup vs baseline: 1.0057x; 1.0057x over previous
.LBB0_1069:
	s_and_b32 s100, s45, 0x700
	s_and_b32 s101, s45, 7
	s_lshl_b32 s101, s101, 5
	s_or_b32 s100, s100, s101
	s_bfe_u32 s101, s45, 0x20006
	s_lshl_b32 s101, s101, 3
	s_or_b32 s100, s100, s101
	s_bfe_u32 s101, s45, 0x30003
	s_or_b32 s100, s100, s101
	s_and_b32 s48, s100, 7
	s_lshl_b32 s49, s48, 2
	s_add_i32 s47, s49, s11
	v_or_b32_e32 v2, s47, v108
	v_lshl_add_u32 v0, v2, 6, v109
	s_ashr_i32 s30, s100, 7
	v_ashrrev_i32_e32 v1, 31, v0
	v_mad_i64_i32 v[102:103], s[12:13], s30, v130, v[0:1]
	v_readlane_b32 s72, v239, 32
	s_bfe_u32 s40, s100, 0x40003
	v_lshlrev_b64 v[0:1], 11, v[102:103]
	v_readlane_b32 s74, v239, 34
	v_readlane_b32 s75, v239, 35
	s_lshl_b32 s22, s40, 7
	s_lshl_b32 s46, s40, 6
	v_lshl_add_u64 v[0:1], s[74:75], 0, v[0:1]
	v_lshl_add_u64 v[0:1], v[0:1], 0, s[22:23]
	v_lshl_add_u64 v[0:1], v[0:1], 0, v[98:99]
	global_load_dwordx4 v[64:67], v[0:1], off
	global_load_dwordx4 v[68:71], v[0:1], off offset:32
	global_load_dwordx4 v[72:75], v[0:1], off offset:64
	global_load_dwordx4 v[76:79], v[0:1], off offset:96
	v_mad_i64_i32 v[0:1], s[12:13], s30, v130, v[92:93]
	s_mul_hi_i32 s13, s30, 0xfffffb00
	s_mulk_i32 s30, 0xfb00
	v_readlane_b32 s76, v239, 36
	v_readlane_b32 s77, v239, 37
	v_lshlrev_b64 v[4:5], 11, v[0:1]
	s_add_u32 s12, s46, s30
	v_lshl_add_u64 v[4:5], s[76:77], 0, v[4:5]
	s_addc_u32 s13, 0, s13
	v_lshl_add_u64 v[4:5], v[4:5], 0, s[22:23]
	v_lshl_add_u64 v[0:1], s[12:13], 0, v[0:1]
	v_lshl_add_u64 v[104:105], v[4:5], 0, v[100:101]
	v_mad_u64_u32 v[106:107], s[12:13], v0, s33, v[96:97]
	v_mad_i32_i24 v107, v1, s33, v107
	global_load_dwordx4 v[80:83], v[104:105], off
	global_load_dwordx4 v[84:87], v[106:107], off
	v_med3_u32 v0, s49, 1, 25
	v_readlane_b32 s73, v239, 33
	v_readfirstlane_b32 s50, v0
	v_readlane_b32 s78, v239, 38
	v_readlane_b32 s79, v239, 39
	s_waitcnt vmcnt(63) expcnt(7) lgkmcnt(15)
	s_barrier
	s_and_saveexec_b64 s[12:13], s[0:1]
	s_cbranch_execz .LBB0_1082
	s_mov_b64 s[38:39], -1
	v_mov_b32_e32 v0, v90
	s_and_saveexec_b64 s[30:31], s[2:3]
	s_cbranch_execz .LBB0_1079
	s_mulk_i32 s40, 0x744
	s_add_u32 s38, s56, s40
	s_addc_u32 s39, s57, 0
	v_mov_b32_e32 v5, 0
	v_mov_b64_e32 v[0:1], v[90:91]
	s_and_saveexec_b64 s[40:41], s[4:5]
	s_cbranch_execz .LBB0_1075
	s_mov_b32 s22, 0
	s_mov_b64 s[42:43], 0
	v_mov_b32_e32 v3, v127
	v_mov_b32_e32 v4, v126
	v_mov_b64_e32 v[0:1], v[90:91]

.LBB0_1079:
	s_or_b64 exec, exec, s[30:31]
	s_and_b64 exec, exec, s[38:39]
	s_cbranch_execz .LBB0_1082
	s_lshr_b32 s22, s100, 3
	s_and_b32 s22, s22, 15
	s_mulk_i32 s22, 0x744
	s_add_u32 s30, s56, s22
	v_ashrrev_i32_e32 v1, 31, v0
	s_addc_u32 s31, s57, 0
	v_add_u32_e32 v3, 0xfffffe00, v0
	v_lshl_add_u32 v4, v0, 2, v132
	v_lshl_add_u64 v[0:1], v[0:1], 2, s[30:31]
	s_mov_b64 s[30:31], 0

.LBB0_1082:
	s_or_b64 exec, exec, s[12:13]
	s_add_i32 s49, s49, -4
	s_cmp_lg_u32 s48, 0
	s_cselect_b32 s22, s49, 0
	s_sub_i32 s38, s50, s22
	s_add_i32 s38, s38, 11
	s_cmp_lt_i32 s38, 1
	s_cbranch_scc1 .LBB0_1067
	s_and_b32 s12, s100, 7
	s_mulk_i32 s12, 0x1f0
	s_mul_i32 s13, s22, 0x7c
	v_med3_i32 v0, s47, 3, 27
	v_med3_i32 v134, v2, 4, 28
	s_sub_i32 s12, s13, s12
	v_med3_i32 v135, s47, 4, 28
	v_add_u32_e32 v136, 5, v0
	v_add_u32_e32 v137, 4, v134
	v_add_u32_e32 v138, s12, v129
	s_mov_b32 s41, 0
	v_mov_b32_e32 v0, v89
	v_mov_b32_e32 v1, v89
	v_mov_b32_e32 v2, v89
	v_mov_b32_e32 v3, v89
	v_mov_b32_e32 v4, v89
	v_mov_b32_e32 v5, v89
	v_mov_b32_e32 v6, v89
	v_mov_b32_e32 v7, v89
	v_mov_b32_e32 v8, v89
	v_mov_b32_e32 v9, v89
	v_mov_b32_e32 v10, v89
	v_mov_b32_e32 v11, v89
	v_mov_b32_e32 v12, v89
	v_mov_b32_e32 v13, v89
	v_mov_b32_e32 v14, v89
	v_mov_b32_e32 v15, v89
	v_mov_b32_e32 v16, v89
	v_mov_b32_e32 v17, v89
	v_mov_b32_e32 v18, v89
	v_mov_b32_e32 v19, v89
	v_mov_b32_e32 v20, v89
	v_mov_b32_e32 v21, v89
	v_mov_b32_e32 v22, v89
	v_mov_b32_e32 v23, v89
	v_mov_b32_e32 v24, v89
	v_mov_b32_e32 v25, v89
	v_mov_b32_e32 v26, v89
	v_mov_b32_e32 v27, v89
	v_mov_b32_e32 v28, v89
	v_mov_b32_e32 v29, v89
	v_mov_b32_e32 v30, v89
	v_mov_b32_e32 v31, v89
	v_mov_b32_e32 v140, 0
	v_mov_b32_e32 v139, 0xff800000
